# K-loop heads aligned to 256 B (on top of noprio/nowait + bal44 + scan norm)
# speedup vs baseline: 1.0106x; 1.0006x over previous
; template <class Epi, class Sched, bool ALIGN_EPI = false, bool SP2 = false>
; __device__ __forceinline__ void gemm_phase(PG8_LAS unsigned char* lds, const Gemm g, const Sched& S, const Epi& E) {
;     ...
;         const bool has_next = S.next(ui + 1, nxt);
;         const char* nA = has_next ? (const char*)g.A + (size_t)nxt.pm * tstep : cA; const char* nB = has_next ? (const char*)g.Bt + (size_t)nxt.pn * tstep : cB;
;         for (int t = 0; t < nt; t += 2) {
;             const bool last = (t == nt - 2);
;             const char* a1 = cA + (size_t)(t + 1) * kstep;
;             const char* a2 = last ? nA : cA + (size_t)(t + 2) * kstep; const char* b2 = last ? nB : cB + (size_t)(t + 2) * kstep;
;     ...
; #pragma unroll
;         for (int a = 0; a < 2; ++a)
; #pragma unroll
;             for (int b = 0; b < 2; ++b)
; #pragma unroll
;                 for (int m = 0; m < 4; ++m)
; #pragma unroll
;                     for (int n = 0; n < 2; ++n) acc[a][b][m][n] = (f32x4){0.f, 0.f, 0.f, 0.f};
;         cur = nxt; cA = nA; cB = nB; ++ui;
.LBB0_179:
	s_ashr_i32 s25, s24, 31
	s_lshl_b64 s[26:27], s[24:25], 21
	s_add_u32 s26, s84, s26
	s_addc_u32 s27, s85, s27
	s_and_b64 s[28:29], s[4:5], exec
	s_cselect_b32 s7, s27, s35
	s_cselect_b32 s25, s26, s34
	s_ashr_i32 s15, s14, 31
	s_lshl_b64 s[28:29], s[14:15], 21
	s_add_u32 s28, s78, s28
	s_addc_u32 s29, s79, s29
	s_and_b64 s[38:39], s[4:5], exec
	s_cselect_b32 s15, s29, s37
	s_cselect_b32 s31, s28, s36
	s_add_u32 s34, s34, 0x100080
	s_addc_u32 s35, s35, 0
	s_add_u32 s54, s36, 0x100
	v_mov_b32_e32 v2, 0
	s_addc_u32 s55, s37, 0
	s_mov_b32 s56, -2
	v_mov_b32_e32 v3, v2
	v_mov_b32_e32 v4, v2
	v_mov_b32_e32 v5, v2
	v_mov_b32_e32 v6, v2
	v_mov_b32_e32 v7, v2
	v_mov_b32_e32 v8, v2
	v_mov_b32_e32 v9, v2
	v_mov_b32_e32 v18, v2
	v_mov_b32_e32 v19, v2
	v_mov_b32_e32 v20, v2
	v_mov_b32_e32 v21, v2
	v_mov_b32_e32 v22, v2
	v_mov_b32_e32 v23, v2
	v_mov_b32_e32 v24, v2
	v_mov_b32_e32 v25, v2
	v_mov_b32_e32 v34, v2
	v_mov_b32_e32 v35, v2
	v_mov_b32_e32 v36, v2
	v_mov_b32_e32 v37, v2
	v_mov_b32_e32 v38, v2
	v_mov_b32_e32 v39, v2
	v_mov_b32_e32 v40, v2
	v_mov_b32_e32 v41, v2
	v_mov_b32_e32 v50, v2
	v_mov_b32_e32 v51, v2
	v_mov_b32_e32 v52, v2
	v_mov_b32_e32 v53, v2
	v_mov_b32_e32 v54, v2
	v_mov_b32_e32 v55, v2
	v_mov_b32_e32 v56, v2
	v_mov_b32_e32 v57, v2
	v_mov_b32_e32 v10, v2
	v_mov_b32_e32 v11, v2
	v_mov_b32_e32 v12, v2
	v_mov_b32_e32 v13, v2
	v_mov_b32_e32 v14, v2
	v_mov_b32_e32 v15, v2
	v_mov_b32_e32 v16, v2
	v_mov_b32_e32 v17, v2
	v_mov_b32_e32 v26, v2
	v_mov_b32_e32 v27, v2
	v_mov_b32_e32 v28, v2
	v_mov_b32_e32 v29, v2
	v_mov_b32_e32 v30, v2
	v_mov_b32_e32 v31, v2
	v_mov_b32_e32 v32, v2
	v_mov_b32_e32 v33, v2
	v_mov_b32_e32 v42, v2
	v_mov_b32_e32 v43, v2
	v_mov_b32_e32 v44, v2
	v_mov_b32_e32 v45, v2
	v_mov_b32_e32 v46, v2
	v_mov_b32_e32 v47, v2
	v_mov_b32_e32 v48, v2
	v_mov_b32_e32 v49, v2
	v_mov_b32_e32 v58, v2
	v_mov_b32_e32 v59, v2
	v_mov_b32_e32 v60, v2
	v_mov_b32_e32 v61, v2
	v_mov_b32_e32 v62, v2
	v_mov_b32_e32 v63, v2
	v_mov_b32_e32 v64, v2
	v_mov_b32_e32 v65, v2
	v_mov_b32_e32 v66, v2
	v_mov_b32_e32 v67, v2
	v_mov_b32_e32 v68, v2
	v_mov_b32_e32 v69, v2
	v_mov_b32_e32 v70, v2
	v_mov_b32_e32 v71, v2
	v_mov_b32_e32 v72, v2
	v_mov_b32_e32 v73, v2
	v_mov_b32_e32 v82, v2
	v_mov_b32_e32 v83, v2
	v_mov_b32_e32 v84, v2
	v_mov_b32_e32 v85, v2
	v_mov_b32_e32 v86, v2
	v_mov_b32_e32 v87, v2
	v_mov_b32_e32 v88, v2
	v_mov_b32_e32 v89, v2
	v_mov_b32_e32 v98, v2
	v_mov_b32_e32 v99, v2
	v_mov_b32_e32 v100, v2
	v_mov_b32_e32 v101, v2
	v_mov_b32_e32 v102, v2
	v_mov_b32_e32 v103, v2
	v_mov_b32_e32 v104, v2
	v_mov_b32_e32 v105, v2
	v_mov_b32_e32 v114, v2
	v_mov_b32_e32 v115, v2
	v_mov_b32_e32 v116, v2
	v_mov_b32_e32 v117, v2
	v_mov_b32_e32 v118, v2
	v_mov_b32_e32 v119, v2
	v_mov_b32_e32 v120, v2
	v_mov_b32_e32 v121, v2
	v_mov_b32_e32 v74, v2
	v_mov_b32_e32 v75, v2
	v_mov_b32_e32 v76, v2
	v_mov_b32_e32 v77, v2
	v_mov_b32_e32 v78, v2
	v_mov_b32_e32 v79, v2
	v_mov_b32_e32 v80, v2
	v_mov_b32_e32 v81, v2
	v_mov_b32_e32 v90, v2
	v_mov_b32_e32 v91, v2
	v_mov_b32_e32 v92, v2
	v_mov_b32_e32 v93, v2
	v_mov_b32_e32 v94, v2
	v_mov_b32_e32 v95, v2
	v_mov_b32_e32 v96, v2
	v_mov_b32_e32 v97, v2
	v_mov_b32_e32 v106, v2
	v_mov_b32_e32 v107, v2
	v_mov_b32_e32 v108, v2
	v_mov_b32_e32 v109, v2
	v_mov_b32_e32 v110, v2
	v_mov_b32_e32 v111, v2
	v_mov_b32_e32 v112, v2
	v_mov_b32_e32 v113, v2
	v_mov_b32_e32 v122, v2
	v_mov_b32_e32 v123, v2
	v_mov_b32_e32 v124, v2
	v_mov_b32_e32 v125, v2
	v_mov_b32_e32 v126, v2
	v_mov_b32_e32 v127, v2
	v_mov_b32_e32 v128, v2
	v_mov_b32_e32 v129, v2
	.p2align 8

; template <class Epi, class Sched, bool ALIGN_EPI = false, bool SP2 = false>
; __device__ __forceinline__ void gemm_phase(PG8_LAS unsigned char* lds, const Gemm g, const Sched& S, const Epi& E) {
;     ...
;         const bool has_next = S.next(ui + 1, nxt);
;         const char* nA = has_next ? (const char*)g.A + (size_t)nxt.pm * tstep : cA; const char* nB = has_next ? (const char*)g.Bt + (size_t)nxt.pn * tstep : cB;
;         for (int t = 0; t < nt; t += 2) {
;             const bool last = (t == nt - 2);
;             const char* a1 = cA + (size_t)(t + 1) * kstep;
;             const char* a2 = last ? nA : cA + (size_t)(t + 2) * kstep; const char* b2 = last ? nB : cB + (size_t)(t + 2) * kstep;
;     ...
; #pragma unroll
;         for (int a = 0; a < 2; ++a)
; #pragma unroll
;             for (int b = 0; b < 2; ++b)
; #pragma unroll
;                 for (int m = 0; m < 4; ++m)
; #pragma unroll
;                     for (int n = 0; n < 2; ++n) acc[a][b][m][n] = (f32x4){0.f, 0.f, 0.f, 0.f};
;         cur = nxt; cA = nA; cB = nB; ++ui;
.LBB0_856:
	s_ashr_i32 s15, s14, 31
	s_lshl_b64 s[24:25], s[14:15], 20
	s_add_u32 s24, s84, s24
	s_addc_u32 s25, s85, s25
	s_and_b64 s[26:27], s[0:1], exec
	s_cselect_b32 s15, s25, s31
	s_cselect_b32 s50, s24, s30
	s_ashr_i32 s13, s12, 31
	s_lshl_b64 s[26:27], s[12:13], 20
	s_add_u32 s26, s20, s26
	s_addc_u32 s27, s21, s27
	s_and_b64 s[36:37], s[0:1], exec
	s_cselect_b32 s13, s27, s35
	s_cselect_b32 s51, s26, s34
	s_add_u32 s30, s30, 0x80080
	s_addc_u32 s31, s31, 0
	s_add_u32 s52, s34, 0x100
	v_mov_b32_e32 v2, 0
	s_addc_u32 s53, s35, 0
	s_mov_b32 s56, -2
	v_mov_b32_e32 v3, v2
	v_mov_b32_e32 v4, v2
	v_mov_b32_e32 v5, v2
	v_mov_b32_e32 v6, v2
	v_mov_b32_e32 v7, v2
	v_mov_b32_e32 v8, v2
	v_mov_b32_e32 v9, v2
	v_mov_b32_e32 v18, v2
	v_mov_b32_e32 v19, v2
	v_mov_b32_e32 v20, v2
	v_mov_b32_e32 v21, v2
	v_mov_b32_e32 v22, v2
	v_mov_b32_e32 v23, v2
	v_mov_b32_e32 v24, v2
	v_mov_b32_e32 v25, v2
	v_mov_b32_e32 v34, v2
	v_mov_b32_e32 v35, v2
	v_mov_b32_e32 v36, v2
	v_mov_b32_e32 v37, v2
	v_mov_b32_e32 v38, v2
	v_mov_b32_e32 v39, v2
	v_mov_b32_e32 v40, v2
	v_mov_b32_e32 v41, v2
	v_mov_b32_e32 v50, v2
	v_mov_b32_e32 v51, v2
	v_mov_b32_e32 v52, v2
	v_mov_b32_e32 v53, v2
	v_mov_b32_e32 v54, v2
	v_mov_b32_e32 v55, v2
	v_mov_b32_e32 v56, v2
	v_mov_b32_e32 v57, v2
	v_mov_b32_e32 v10, v2
	v_mov_b32_e32 v11, v2
	v_mov_b32_e32 v12, v2
	v_mov_b32_e32 v13, v2
	v_mov_b32_e32 v14, v2
	v_mov_b32_e32 v15, v2
	v_mov_b32_e32 v16, v2
	v_mov_b32_e32 v17, v2
	v_mov_b32_e32 v26, v2
	v_mov_b32_e32 v27, v2
	v_mov_b32_e32 v28, v2
	v_mov_b32_e32 v29, v2
	v_mov_b32_e32 v30, v2
	v_mov_b32_e32 v31, v2
	v_mov_b32_e32 v32, v2
	v_mov_b32_e32 v33, v2
	v_mov_b32_e32 v42, v2
	v_mov_b32_e32 v43, v2
	v_mov_b32_e32 v44, v2
	v_mov_b32_e32 v45, v2
	v_mov_b32_e32 v46, v2
	v_mov_b32_e32 v47, v2
	v_mov_b32_e32 v48, v2
	v_mov_b32_e32 v49, v2
	v_mov_b32_e32 v58, v2
	v_mov_b32_e32 v59, v2
	v_mov_b32_e32 v60, v2
	v_mov_b32_e32 v61, v2
	v_mov_b32_e32 v62, v2
	v_mov_b32_e32 v63, v2
	v_mov_b32_e32 v64, v2
	v_mov_b32_e32 v65, v2
	v_mov_b32_e32 v66, v2
	v_mov_b32_e32 v67, v2
	v_mov_b32_e32 v68, v2
	v_mov_b32_e32 v69, v2
	v_mov_b32_e32 v70, v2
	v_mov_b32_e32 v71, v2
	v_mov_b32_e32 v72, v2
	v_mov_b32_e32 v73, v2
	v_mov_b32_e32 v82, v2
	v_mov_b32_e32 v83, v2
	v_mov_b32_e32 v84, v2
	v_mov_b32_e32 v85, v2
	v_mov_b32_e32 v86, v2
	v_mov_b32_e32 v87, v2
	v_mov_b32_e32 v88, v2
	v_mov_b32_e32 v89, v2
	v_mov_b32_e32 v98, v2
	v_mov_b32_e32 v99, v2
	v_mov_b32_e32 v100, v2
	v_mov_b32_e32 v101, v2
	v_mov_b32_e32 v102, v2
	v_mov_b32_e32 v103, v2
	v_mov_b32_e32 v104, v2
	v_mov_b32_e32 v105, v2
	v_mov_b32_e32 v114, v2
	v_mov_b32_e32 v115, v2
	v_mov_b32_e32 v116, v2
	v_mov_b32_e32 v117, v2
	v_mov_b32_e32 v118, v2
	v_mov_b32_e32 v119, v2
	v_mov_b32_e32 v120, v2
	v_mov_b32_e32 v121, v2
	v_mov_b32_e32 v74, v2
	v_mov_b32_e32 v75, v2
	v_mov_b32_e32 v76, v2
	v_mov_b32_e32 v77, v2
	v_mov_b32_e32 v78, v2
	v_mov_b32_e32 v79, v2
	v_mov_b32_e32 v80, v2
	v_mov_b32_e32 v81, v2
	v_mov_b32_e32 v90, v2
	v_mov_b32_e32 v91, v2
	v_mov_b32_e32 v92, v2
	v_mov_b32_e32 v93, v2
	v_mov_b32_e32 v94, v2
	v_mov_b32_e32 v95, v2
	v_mov_b32_e32 v96, v2
	v_mov_b32_e32 v97, v2
	v_mov_b32_e32 v106, v2
	v_mov_b32_e32 v107, v2
	v_mov_b32_e32 v108, v2
	v_mov_b32_e32 v109, v2
	v_mov_b32_e32 v110, v2
	v_mov_b32_e32 v111, v2
	v_mov_b32_e32 v112, v2
	v_mov_b32_e32 v113, v2
	v_mov_b32_e32 v122, v2
	v_mov_b32_e32 v123, v2
	v_mov_b32_e32 v124, v2
	v_mov_b32_e32 v125, v2
	v_mov_b32_e32 v126, v2
	v_mov_b32_e32 v127, v2
	v_mov_b32_e32 v128, v2
	v_mov_b32_e32 v129, v2
	.p2align 8

; template <class Epi, class Sched, bool ALIGN_EPI = false, bool SP2 = false>
; __device__ __forceinline__ void gemm_phase(PG8_LAS unsigned char* lds, const Gemm g, const Sched& S, const Epi& E) {
;     ...
;         const bool has_next = S.next(ui + 1, nxt);
;         const char* nA = has_next ? (const char*)g.A + (size_t)nxt.pm * tstep : cA; const char* nB = has_next ? (const char*)g.Bt + (size_t)nxt.pn * tstep : cB;
;         for (int t = 0; t < nt; t += 2) {
;             const bool last = (t == nt - 2);
;             const char* a1 = cA + (size_t)(t + 1) * kstep;
;             const char* a2 = last ? nA : cA + (size_t)(t + 2) * kstep; const char* b2 = last ? nB : cB + (size_t)(t + 2) * kstep;
;     ...
; #pragma unroll
;         for (int a = 0; a < 2; ++a)
; #pragma unroll
;             for (int b = 0; b < 2; ++b)
; #pragma unroll
;                 for (int m = 0; m < 4; ++m)
; #pragma unroll
;                     for (int n = 0; n < 2; ++n) acc[a][b][m][n] = (f32x4){0.f, 0.f, 0.f, 0.f};
;         cur = nxt; cA = nA; cB = nB; ++ui;
.LBB0_883:
	s_ashr_i32 s15, s14, 31
	s_lshl_b64 s[24:25], s[14:15], 20
	s_add_u32 s24, s54, s24
	s_addc_u32 s25, s55, s25
	s_and_b64 s[26:27], s[0:1], exec
	s_cselect_b32 s15, s25, s31
	s_cselect_b32 s50, s24, s30
	s_ashr_i32 s13, s12, 31
	s_lshl_b64 s[26:27], s[12:13], 20
	s_add_u32 s26, s18, s26
	s_addc_u32 s27, s19, s27
	s_and_b64 s[36:37], s[0:1], exec
	s_cselect_b32 s13, s27, s35
	s_cselect_b32 s51, s26, s34
	s_add_u32 s30, s30, 0x80080
	s_addc_u32 s31, s31, 0
	s_add_u32 s52, s34, 0x100
	v_mov_b32_e32 v2, 0
	s_addc_u32 s53, s35, 0
	s_mov_b32 s56, -2
	v_mov_b32_e32 v3, v2
	v_mov_b32_e32 v4, v2
	v_mov_b32_e32 v5, v2
	v_mov_b32_e32 v6, v2
	v_mov_b32_e32 v7, v2
	v_mov_b32_e32 v8, v2
	v_mov_b32_e32 v9, v2
	v_mov_b32_e32 v18, v2
	v_mov_b32_e32 v19, v2
	v_mov_b32_e32 v20, v2
	v_mov_b32_e32 v21, v2
	v_mov_b32_e32 v22, v2
	v_mov_b32_e32 v23, v2
	v_mov_b32_e32 v24, v2
	v_mov_b32_e32 v25, v2
	v_mov_b32_e32 v34, v2
	v_mov_b32_e32 v35, v2
	v_mov_b32_e32 v36, v2
	v_mov_b32_e32 v37, v2
	v_mov_b32_e32 v38, v2
	v_mov_b32_e32 v39, v2
	v_mov_b32_e32 v40, v2
	v_mov_b32_e32 v41, v2
	v_mov_b32_e32 v50, v2
	v_mov_b32_e32 v51, v2
	v_mov_b32_e32 v52, v2
	v_mov_b32_e32 v53, v2
	v_mov_b32_e32 v54, v2
	v_mov_b32_e32 v55, v2
	v_mov_b32_e32 v56, v2
	v_mov_b32_e32 v57, v2
	v_mov_b32_e32 v10, v2
	v_mov_b32_e32 v11, v2
	v_mov_b32_e32 v12, v2
	v_mov_b32_e32 v13, v2
	v_mov_b32_e32 v14, v2
	v_mov_b32_e32 v15, v2
	v_mov_b32_e32 v16, v2
	v_mov_b32_e32 v17, v2
	v_mov_b32_e32 v26, v2
	v_mov_b32_e32 v27, v2
	v_mov_b32_e32 v28, v2
	v_mov_b32_e32 v29, v2
	v_mov_b32_e32 v30, v2
	v_mov_b32_e32 v31, v2
	v_mov_b32_e32 v32, v2
	v_mov_b32_e32 v33, v2
	v_mov_b32_e32 v42, v2
	v_mov_b32_e32 v43, v2
	v_mov_b32_e32 v44, v2
	v_mov_b32_e32 v45, v2
	v_mov_b32_e32 v46, v2
	v_mov_b32_e32 v47, v2
	v_mov_b32_e32 v48, v2
	v_mov_b32_e32 v49, v2
	v_mov_b32_e32 v58, v2
	v_mov_b32_e32 v59, v2
	v_mov_b32_e32 v60, v2
	v_mov_b32_e32 v61, v2
	v_mov_b32_e32 v62, v2
	v_mov_b32_e32 v63, v2
	v_mov_b32_e32 v64, v2
	v_mov_b32_e32 v65, v2
	v_mov_b32_e32 v66, v2
	v_mov_b32_e32 v67, v2
	v_mov_b32_e32 v68, v2
	v_mov_b32_e32 v69, v2
	v_mov_b32_e32 v70, v2
	v_mov_b32_e32 v71, v2
	v_mov_b32_e32 v72, v2
	v_mov_b32_e32 v73, v2
	v_mov_b32_e32 v82, v2
	v_mov_b32_e32 v83, v2
	v_mov_b32_e32 v84, v2
	v_mov_b32_e32 v85, v2
	v_mov_b32_e32 v86, v2
	v_mov_b32_e32 v87, v2
	v_mov_b32_e32 v88, v2
	v_mov_b32_e32 v89, v2
	v_mov_b32_e32 v98, v2
	v_mov_b32_e32 v99, v2
	v_mov_b32_e32 v100, v2
	v_mov_b32_e32 v101, v2
	v_mov_b32_e32 v102, v2
	v_mov_b32_e32 v103, v2
	v_mov_b32_e32 v104, v2
	v_mov_b32_e32 v105, v2
	v_mov_b32_e32 v114, v2
	v_mov_b32_e32 v115, v2
	v_mov_b32_e32 v116, v2
	v_mov_b32_e32 v117, v2
	v_mov_b32_e32 v118, v2
	v_mov_b32_e32 v119, v2
	v_mov_b32_e32 v120, v2
	v_mov_b32_e32 v121, v2
	v_mov_b32_e32 v74, v2
	v_mov_b32_e32 v75, v2
	v_mov_b32_e32 v76, v2
	v_mov_b32_e32 v77, v2
	v_mov_b32_e32 v78, v2
	v_mov_b32_e32 v79, v2
	v_mov_b32_e32 v80, v2
	v_mov_b32_e32 v81, v2
	v_mov_b32_e32 v90, v2
	v_mov_b32_e32 v91, v2
	v_mov_b32_e32 v92, v2
	v_mov_b32_e32 v93, v2
	v_mov_b32_e32 v94, v2
	v_mov_b32_e32 v95, v2
	v_mov_b32_e32 v96, v2
	v_mov_b32_e32 v97, v2
	v_mov_b32_e32 v106, v2
	v_mov_b32_e32 v107, v2
	v_mov_b32_e32 v108, v2
	v_mov_b32_e32 v109, v2
	v_mov_b32_e32 v110, v2
	v_mov_b32_e32 v111, v2
	v_mov_b32_e32 v112, v2
	v_mov_b32_e32 v113, v2
	v_mov_b32_e32 v122, v2
	v_mov_b32_e32 v123, v2
	v_mov_b32_e32 v124, v2
	v_mov_b32_e32 v125, v2
	v_mov_b32_e32 v126, v2
	v_mov_b32_e32 v127, v2
	v_mov_b32_e32 v128, v2
	v_mov_b32_e32 v129, v2
	s_waitcnt vmcnt(0)
	.p2align 8

; template <class Epi, class Sched, bool ALIGN_EPI = false, bool SP2 = false>
; __device__ __forceinline__ void gemm_phase(PG8_LAS unsigned char* lds, const Gemm g, const Sched& S, const Epi& E) {
;     ...
;         const bool has_next = S.next(ui + 1, nxt);
;         const char* nA = has_next ? (const char*)g.A + (size_t)nxt.pm * tstep : cA; const char* nB = has_next ? (const char*)g.Bt + (size_t)nxt.pn * tstep : cB;
;         for (int t = 0; t < nt; t += 2) {
;             const bool last = (t == nt - 2);
;             const char* a1 = cA + (size_t)(t + 1) * kstep;
;             const char* a2 = last ? nA : cA + (size_t)(t + 2) * kstep; const char* b2 = last ? nB : cB + (size_t)(t + 2) * kstep;
;     ...
; #pragma unroll
;         for (int a = 0; a < 2; ++a)
; #pragma unroll
;             for (int b = 0; b < 2; ++b)
; #pragma unroll
;                 for (int m = 0; m < 4; ++m)
; #pragma unroll
;                     for (int n = 0; n < 2; ++n) acc[a][b][m][n] = (f32x4){0.f, 0.f, 0.f, 0.f};
;         cur = nxt; cA = nA; cB = nB; ++ui;
.LBB0_958:
	s_ashr_i32 s13, s12, 31
	s_lshl_b64 s[14:15], s[12:13], 21
	s_add_u32 s14, s78, s14
	s_addc_u32 s15, s79, s15
	s_and_b64 s[24:25], s[0:1], exec
	s_cselect_b32 s13, s15, s29
	s_cselect_b32 s47, s14, s28
	s_ashr_i32 s11, s10, 31
	s_lshl_b64 s[24:25], s[10:11], 21
	s_add_u32 s24, s16, s24
	s_addc_u32 s25, s17, s25
	s_and_b64 s[34:35], s[0:1], exec
	s_cselect_b32 s11, s25, s31
	s_cselect_b32 s48, s24, s30
	s_add_u32 s28, s28, 0x100080
	s_addc_u32 s29, s29, 0
	s_add_u32 s49, s30, 0x100
	v_mov_b32_e32 v2, 0
	s_addc_u32 s50, s31, 0
	s_mov_b32 s51, -2
	v_mov_b32_e32 v3, v2
	v_mov_b32_e32 v4, v2
	v_mov_b32_e32 v5, v2
	v_mov_b32_e32 v6, v2
	v_mov_b32_e32 v7, v2
	v_mov_b32_e32 v8, v2
	v_mov_b32_e32 v9, v2
	v_mov_b32_e32 v14, v2
	v_mov_b32_e32 v15, v2
	v_mov_b32_e32 v16, v2
	v_mov_b32_e32 v17, v2
	v_mov_b32_e32 v22, v2
	v_mov_b32_e32 v23, v2
	v_mov_b32_e32 v24, v2
	v_mov_b32_e32 v25, v2
	v_mov_b32_e32 v30, v2
	v_mov_b32_e32 v31, v2
	v_mov_b32_e32 v32, v2
	v_mov_b32_e32 v33, v2
	v_mov_b32_e32 v38, v2
	v_mov_b32_e32 v39, v2
	v_mov_b32_e32 v40, v2
	v_mov_b32_e32 v41, v2
	v_mov_b32_e32 v46, v2
	v_mov_b32_e32 v47, v2
	v_mov_b32_e32 v48, v2
	v_mov_b32_e32 v49, v2
	v_mov_b32_e32 v54, v2
	v_mov_b32_e32 v55, v2
	v_mov_b32_e32 v56, v2
	v_mov_b32_e32 v57, v2
	v_mov_b32_e32 v10, v2
	v_mov_b32_e32 v11, v2
	v_mov_b32_e32 v12, v2
	v_mov_b32_e32 v13, v2
	v_mov_b32_e32 v18, v2
	v_mov_b32_e32 v19, v2
	v_mov_b32_e32 v20, v2
	v_mov_b32_e32 v21, v2
	v_mov_b32_e32 v26, v2
	v_mov_b32_e32 v27, v2
	v_mov_b32_e32 v28, v2
	v_mov_b32_e32 v29, v2
	v_mov_b32_e32 v34, v2
	v_mov_b32_e32 v35, v2
	v_mov_b32_e32 v36, v2
	v_mov_b32_e32 v37, v2
	v_mov_b32_e32 v42, v2
	v_mov_b32_e32 v43, v2
	v_mov_b32_e32 v44, v2
	v_mov_b32_e32 v45, v2
	v_mov_b32_e32 v50, v2
	v_mov_b32_e32 v51, v2
	v_mov_b32_e32 v52, v2
	v_mov_b32_e32 v53, v2
	v_mov_b32_e32 v58, v2
	v_mov_b32_e32 v59, v2
	v_mov_b32_e32 v60, v2
	v_mov_b32_e32 v61, v2
	v_mov_b32_e32 v62, v2
	v_mov_b32_e32 v63, v2
	v_mov_b32_e32 v64, v2
	v_mov_b32_e32 v65, v2
	v_mov_b32_e32 v66, v2
	v_mov_b32_e32 v67, v2
	v_mov_b32_e32 v68, v2
	v_mov_b32_e32 v69, v2
	v_mov_b32_e32 v70, v2
	v_mov_b32_e32 v71, v2
	v_mov_b32_e32 v72, v2
	v_mov_b32_e32 v73, v2
	v_mov_b32_e32 v78, v2
	v_mov_b32_e32 v79, v2
	v_mov_b32_e32 v80, v2
	v_mov_b32_e32 v81, v2
	v_mov_b32_e32 v86, v2
	v_mov_b32_e32 v87, v2
	v_mov_b32_e32 v88, v2
	v_mov_b32_e32 v89, v2
	v_mov_b32_e32 v90, v2
	v_mov_b32_e32 v91, v2
	v_mov_b32_e32 v92, v2
	v_mov_b32_e32 v93, v2
	v_mov_b32_e32 v94, v2
	v_mov_b32_e32 v95, v2
	v_mov_b32_e32 v96, v2
	v_mov_b32_e32 v97, v2
	v_mov_b32_e32 v98, v2
	v_mov_b32_e32 v99, v2
	v_mov_b32_e32 v100, v2
	v_mov_b32_e32 v101, v2
	v_mov_b32_e32 v106, v2
	v_mov_b32_e32 v107, v2
	v_mov_b32_e32 v108, v2
	v_mov_b32_e32 v109, v2
	v_mov_b32_e32 v74, v2
	v_mov_b32_e32 v75, v2
	v_mov_b32_e32 v76, v2
	v_mov_b32_e32 v77, v2
	v_mov_b32_e32 v82, v2
	v_mov_b32_e32 v83, v2
	v_mov_b32_e32 v84, v2
	v_mov_b32_e32 v85, v2
	v_mov_b32_e32 v102, v2
	v_mov_b32_e32 v103, v2
	v_mov_b32_e32 v104, v2
	v_mov_b32_e32 v105, v2
	v_mov_b32_e32 v110, v2
	v_mov_b32_e32 v111, v2
	v_mov_b32_e32 v112, v2
	v_mov_b32_e32 v113, v2
	v_mov_b32_e32 v114, v2
	v_mov_b32_e32 v115, v2
	v_mov_b32_e32 v116, v2
	v_mov_b32_e32 v117, v2
	v_mov_b32_e32 v118, v2
	v_mov_b32_e32 v119, v2
	v_mov_b32_e32 v120, v2
	v_mov_b32_e32 v121, v2
	v_mov_b32_e32 v122, v2
	v_mov_b32_e32 v123, v2
	v_mov_b32_e32 v124, v2
	v_mov_b32_e32 v125, v2
	v_mov_b32_e32 v126, v2
	v_mov_b32_e32 v127, v2
	v_mov_b32_e32 v128, v2
	v_mov_b32_e32 v129, v2
	.p2align 8

; template <class Epi, class Sched, bool ALIGN_EPI = false, bool SP2 = false>
; __device__ __forceinline__ void gemm_phase(PG8_LAS unsigned char* lds, const Gemm g, const Sched& S, const Epi& E) {
;     ...
;         const bool has_next = S.next(ui + 1, nxt);
;         const char* nA = has_next ? (const char*)g.A + (size_t)nxt.pm * tstep : cA; const char* nB = has_next ? (const char*)g.Bt + (size_t)nxt.pn * tstep : cB;
;         for (int t = 0; t < nt; t += 2) {
;             const bool last = (t == nt - 2);
;             const char* a1 = cA + (size_t)(t + 1) * kstep;
;             const char* a2 = last ? nA : cA + (size_t)(t + 2) * kstep; const char* b2 = last ? nB : cB + (size_t)(t + 2) * kstep;
;     ...
; #pragma unroll
;         for (int a = 0; a < 2; ++a)
; #pragma unroll
;             for (int b = 0; b < 2; ++b)
; #pragma unroll
;                 for (int m = 0; m < 4; ++m)
; #pragma unroll
;                     for (int n = 0; n < 2; ++n) acc[a][b][m][n] = (f32x4){0.f, 0.f, 0.f, 0.f};
;         cur = nxt; cA = nA; cB = nB; ++ui;
.LBB0_1080:
	s_ashr_i32 s15, s14, 31
	s_lshl_b64 s[24:25], s[14:15], 21
	s_add_u32 s24, s86, s24
	s_addc_u32 s25, s87, s25
	s_and_b64 s[26:27], s[0:1], exec
	s_cselect_b32 s15, s25, s31
	s_cselect_b32 s51, s24, s30
	s_ashr_i32 s13, s12, 31
	s_lshl_b64 s[26:27], s[12:13], 21
	v_readlane_b32 s36, v254, 29
	v_readlane_b32 s37, v254, 30
	s_add_u32 s26, s36, s26
	s_addc_u32 s27, s37, s27
	s_and_b64 s[36:37], s[0:1], exec
	s_cselect_b32 s13, s27, s35
	s_cselect_b32 s52, s26, s34
	s_add_u32 s30, s30, 0x100080
	s_addc_u32 s31, s31, 0
	s_add_u32 s53, s34, 0x100
	v_mov_b32_e32 v2, 0
	s_addc_u32 s54, s35, 0
	s_mov_b32 s55, -2
	v_mov_b32_e32 v3, v2
	v_mov_b32_e32 v4, v2
	v_mov_b32_e32 v5, v2
	v_mov_b32_e32 v6, v2
	v_mov_b32_e32 v7, v2
	v_mov_b32_e32 v8, v2
	v_mov_b32_e32 v9, v2
	v_mov_b32_e32 v18, v2
	v_mov_b32_e32 v19, v2
	v_mov_b32_e32 v20, v2
	v_mov_b32_e32 v21, v2
	v_mov_b32_e32 v22, v2
	v_mov_b32_e32 v23, v2
	v_mov_b32_e32 v24, v2
	v_mov_b32_e32 v25, v2
	v_mov_b32_e32 v34, v2
	v_mov_b32_e32 v35, v2
	v_mov_b32_e32 v36, v2
	v_mov_b32_e32 v37, v2
	v_mov_b32_e32 v38, v2
	v_mov_b32_e32 v39, v2
	v_mov_b32_e32 v40, v2
	v_mov_b32_e32 v41, v2
	v_mov_b32_e32 v50, v2
	v_mov_b32_e32 v51, v2
	v_mov_b32_e32 v52, v2
	v_mov_b32_e32 v53, v2
	v_mov_b32_e32 v54, v2
	v_mov_b32_e32 v55, v2
	v_mov_b32_e32 v56, v2
	v_mov_b32_e32 v57, v2
	v_mov_b32_e32 v10, v2
	v_mov_b32_e32 v11, v2
	v_mov_b32_e32 v12, v2
	v_mov_b32_e32 v13, v2
	v_mov_b32_e32 v14, v2
	v_mov_b32_e32 v15, v2
	v_mov_b32_e32 v16, v2
	v_mov_b32_e32 v17, v2
	v_mov_b32_e32 v26, v2
	v_mov_b32_e32 v27, v2
	v_mov_b32_e32 v28, v2
	v_mov_b32_e32 v29, v2
	v_mov_b32_e32 v30, v2
	v_mov_b32_e32 v31, v2
	v_mov_b32_e32 v32, v2
	v_mov_b32_e32 v33, v2
	v_mov_b32_e32 v42, v2
	v_mov_b32_e32 v43, v2
	v_mov_b32_e32 v44, v2
	v_mov_b32_e32 v45, v2
	v_mov_b32_e32 v46, v2
	v_mov_b32_e32 v47, v2
	v_mov_b32_e32 v48, v2
	v_mov_b32_e32 v49, v2
	v_mov_b32_e32 v58, v2
	v_mov_b32_e32 v59, v2
	v_mov_b32_e32 v60, v2
	v_mov_b32_e32 v61, v2
	v_mov_b32_e32 v62, v2
	v_mov_b32_e32 v63, v2
	v_mov_b32_e32 v64, v2
	v_mov_b32_e32 v65, v2
	v_mov_b32_e32 v66, v2
	v_mov_b32_e32 v67, v2
	v_mov_b32_e32 v68, v2
	v_mov_b32_e32 v69, v2
	v_mov_b32_e32 v70, v2
	v_mov_b32_e32 v71, v2
	v_mov_b32_e32 v72, v2
	v_mov_b32_e32 v73, v2
	v_mov_b32_e32 v82, v2
	v_mov_b32_e32 v83, v2
	v_mov_b32_e32 v84, v2
	v_mov_b32_e32 v85, v2
	v_mov_b32_e32 v86, v2
	v_mov_b32_e32 v87, v2
	v_mov_b32_e32 v88, v2
	v_mov_b32_e32 v89, v2
	v_mov_b32_e32 v98, v2
	v_mov_b32_e32 v99, v2
	v_mov_b32_e32 v100, v2
	v_mov_b32_e32 v101, v2
	v_mov_b32_e32 v102, v2
	v_mov_b32_e32 v103, v2
	v_mov_b32_e32 v104, v2
	v_mov_b32_e32 v105, v2
	v_mov_b32_e32 v114, v2
	v_mov_b32_e32 v115, v2
	v_mov_b32_e32 v116, v2
	v_mov_b32_e32 v117, v2
	v_mov_b32_e32 v118, v2
	v_mov_b32_e32 v119, v2
	v_mov_b32_e32 v120, v2
	v_mov_b32_e32 v121, v2
	v_mov_b32_e32 v74, v2
	v_mov_b32_e32 v75, v2
	v_mov_b32_e32 v76, v2
	v_mov_b32_e32 v77, v2
	v_mov_b32_e32 v78, v2
	v_mov_b32_e32 v79, v2
	v_mov_b32_e32 v80, v2
	v_mov_b32_e32 v81, v2
	v_mov_b32_e32 v90, v2
	v_mov_b32_e32 v91, v2
	v_mov_b32_e32 v92, v2
	v_mov_b32_e32 v93, v2
	v_mov_b32_e32 v94, v2
	v_mov_b32_e32 v95, v2
	v_mov_b32_e32 v96, v2
	v_mov_b32_e32 v97, v2
	v_mov_b32_e32 v106, v2
	v_mov_b32_e32 v107, v2
	v_mov_b32_e32 v108, v2
	v_mov_b32_e32 v109, v2
	v_mov_b32_e32 v110, v2
	v_mov_b32_e32 v111, v2
	v_mov_b32_e32 v112, v2
	v_mov_b32_e32 v113, v2
	v_mov_b32_e32 v122, v2
	v_mov_b32_e32 v123, v2
	v_mov_b32_e32 v124, v2
	v_mov_b32_e32 v125, v2
	v_mov_b32_e32 v126, v2
	v_mov_b32_e32 v127, v2
	v_mov_b32_e32 v128, v2
	v_mov_b32_e32 v129, v2
	.p2align 8

; template <class Epi, class Sched, bool ALIGN_EPI = false, bool SP2 = false>
; __device__ __forceinline__ void gemm_phase(PG8_LAS unsigned char* lds, const Gemm g, const Sched& S, const Epi& E) {
;     ...
;         for (int t = 0; t < nt; t += 2) {
;             const bool last = (t == nt - 2);
;             const char* a1 = cA + (size_t)(t + 1) * kstep;
;             const char* a2 = last ? nA : cA + (size_t)(t + 2) * kstep; const char* b2 = last ? nB : cB + (size_t)(t + 2) * kstep;
;     ...
; #pragma unroll
;         for (int a = 0; a < 2; ++a)
; #pragma unroll
;             for (int b = 0; b < 2; ++b)
; #pragma unroll
;                 for (int m = 0; m < 4; ++m)
; #pragma unroll
;                     for (int n = 0; n < 2; ++n) acc[a][b][m][n] = (f32x4){0.f, 0.f, 0.f, 0.f};
;         cur = nxt; cA = nA; cB = nB; ++ui;
.LBB0_1163:
	s_add_u32 s14, s14, 0x2b0080
	s_addc_u32 s15, s15, 0
	s_add_u32 s39, s16, 0x100
	v_mov_b32_e32 v0, 0
	s_addc_u32 s40, s17, 0
	s_mov_b32 s41, -2
	v_mov_b32_e32 v1, v0
	v_mov_b32_e32 v2, v0
	v_mov_b32_e32 v3, v0
	v_mov_b32_e32 v4, v0
	v_mov_b32_e32 v5, v0
	v_mov_b32_e32 v6, v0
	v_mov_b32_e32 v7, v0
	v_mov_b32_e32 v12, v0
	v_mov_b32_e32 v13, v0
	v_mov_b32_e32 v14, v0
	v_mov_b32_e32 v15, v0
	v_mov_b32_e32 v20, v0
	v_mov_b32_e32 v21, v0
	v_mov_b32_e32 v22, v0
	v_mov_b32_e32 v23, v0
	v_mov_b32_e32 v28, v0
	v_mov_b32_e32 v29, v0
	v_mov_b32_e32 v30, v0
	v_mov_b32_e32 v31, v0
	v_mov_b32_e32 v36, v0
	v_mov_b32_e32 v37, v0
	v_mov_b32_e32 v38, v0
	v_mov_b32_e32 v39, v0
	v_mov_b32_e32 v44, v0
	v_mov_b32_e32 v45, v0
	v_mov_b32_e32 v46, v0
	v_mov_b32_e32 v47, v0
	v_mov_b32_e32 v52, v0
	v_mov_b32_e32 v53, v0
	v_mov_b32_e32 v54, v0
	v_mov_b32_e32 v55, v0
	v_mov_b32_e32 v8, v0
	v_mov_b32_e32 v9, v0
	v_mov_b32_e32 v10, v0
	v_mov_b32_e32 v11, v0
	v_mov_b32_e32 v16, v0
	v_mov_b32_e32 v17, v0
	v_mov_b32_e32 v18, v0
	v_mov_b32_e32 v19, v0
	v_mov_b32_e32 v24, v0
	v_mov_b32_e32 v25, v0
	v_mov_b32_e32 v26, v0
	v_mov_b32_e32 v27, v0
	v_mov_b32_e32 v32, v0
	v_mov_b32_e32 v33, v0
	v_mov_b32_e32 v34, v0
	v_mov_b32_e32 v35, v0
	v_mov_b32_e32 v40, v0
	v_mov_b32_e32 v41, v0
	v_mov_b32_e32 v42, v0
	v_mov_b32_e32 v43, v0
	v_mov_b32_e32 v48, v0
	v_mov_b32_e32 v49, v0
	v_mov_b32_e32 v50, v0
	v_mov_b32_e32 v51, v0
	v_mov_b32_e32 v56, v0
	v_mov_b32_e32 v57, v0
	v_mov_b32_e32 v58, v0
	v_mov_b32_e32 v59, v0
	v_mov_b32_e32 v60, v0
	v_mov_b32_e32 v61, v0
	v_mov_b32_e32 v62, v0
	v_mov_b32_e32 v63, v0
	v_mov_b32_e32 v64, v0
	v_mov_b32_e32 v65, v0
	v_mov_b32_e32 v66, v0
	v_mov_b32_e32 v67, v0
	v_mov_b32_e32 v68, v0
	v_mov_b32_e32 v69, v0
	v_mov_b32_e32 v70, v0
	v_mov_b32_e32 v71, v0
	v_mov_b32_e32 v76, v0
	v_mov_b32_e32 v77, v0
	v_mov_b32_e32 v78, v0
	v_mov_b32_e32 v79, v0
	v_mov_b32_e32 v84, v0
	v_mov_b32_e32 v85, v0
	v_mov_b32_e32 v86, v0
	v_mov_b32_e32 v87, v0
	v_mov_b32_e32 v92, v0
	v_mov_b32_e32 v93, v0
	v_mov_b32_e32 v94, v0
	v_mov_b32_e32 v95, v0
	v_mov_b32_e32 v100, v0
	v_mov_b32_e32 v101, v0
	v_mov_b32_e32 v102, v0
	v_mov_b32_e32 v103, v0
	v_mov_b32_e32 v108, v0
	v_mov_b32_e32 v109, v0
	v_mov_b32_e32 v110, v0
	v_mov_b32_e32 v111, v0
	v_mov_b32_e32 v116, v0
	v_mov_b32_e32 v117, v0
	v_mov_b32_e32 v118, v0
	v_mov_b32_e32 v119, v0
	v_mov_b32_e32 v72, v0
	v_mov_b32_e32 v73, v0
	v_mov_b32_e32 v74, v0
	v_mov_b32_e32 v75, v0
	v_mov_b32_e32 v80, v0
	v_mov_b32_e32 v81, v0
	v_mov_b32_e32 v82, v0
	v_mov_b32_e32 v83, v0
	v_mov_b32_e32 v88, v0
	v_mov_b32_e32 v89, v0
	v_mov_b32_e32 v90, v0
	v_mov_b32_e32 v91, v0
	v_mov_b32_e32 v96, v0
	v_mov_b32_e32 v97, v0
	v_mov_b32_e32 v98, v0
	v_mov_b32_e32 v99, v0
	v_mov_b32_e32 v104, v0
	v_mov_b32_e32 v105, v0
	v_mov_b32_e32 v106, v0
	v_mov_b32_e32 v107, v0
	v_mov_b32_e32 v112, v0
	v_mov_b32_e32 v113, v0
	v_mov_b32_e32 v114, v0
	v_mov_b32_e32 v115, v0
	v_mov_b32_e32 v120, v0
	v_mov_b32_e32 v121, v0
	v_mov_b32_e32 v122, v0
	v_mov_b32_e32 v123, v0
	v_mov_b32_e32 v124, v0
	v_mov_b32_e32 v125, v0
	v_mov_b32_e32 v126, v0
	v_mov_b32_e32 v127, v0
	s_waitcnt vmcnt(0)
	.p2align 8
